# v29 + P1 shift-bound maxima: one workgroup per sublayer, 8 waves x 4 columns, overlapped 68-load batches, LDS combine (was 6 waves x 16 serial load rounds)
# speedup vs baseline: 1.0002x; 1.0002x over previous
.LBB0_133:
	s_or_b64 exec, exec, s[16:17]
	s_add_i32 s4, s22, -24
	s_cmp_gt_u32 s4, 5
	s_cbranch_scc1 .LBB0_143
	s_lshr_b32 s5, s23, 6
	s_mul_i32 s10, s4, 0x1800
	s_lshl_b32 s11, s5, 8
	s_add_i32 s10, s10, s11
	v_and_b32_e32 v2, 63, v1
	v_add_u32_e32 v4, s10, v2
	v_lshlrev_b32_e32 v4, 2, v4
	v_lshlrev_b32_e32 v5, 2, v1
	v_mov_b32_e32 v3, 0
	s_add_u32 s16, s14, 0x24000
	s_addc_u32 s17, s15, 0
	s_add_u32 s18, s16, 0x24000
	s_addc_u32 s19, s17, 0
	s_add_u32 s20, s18, 0x24000
	s_addc_u32 s21, s19, 0
	s_add_u32 s26, s20, 0x24000
	s_addc_u32 s27, s21, 0
	s_add_u32 s28, s26, 0x24000
	s_addc_u32 s29, s27, 0
	s_add_u32 s30, s28, 0x24000
	s_addc_u32 s31, s29, 0
	s_add_u32 s34, s30, 0x24000
	s_addc_u32 s35, s31, 0
	s_add_u32 s36, s34, 0x24000
	s_addc_u32 s37, s35, 0
	s_add_u32 s38, s36, 0x24000
	s_addc_u32 s39, s37, 0
	s_add_u32 s40, s38, 0x24000
	s_addc_u32 s41, s39, 0
	s_add_u32 s42, s40, 0x24000
	s_addc_u32 s43, s41, 0
	s_add_u32 s44, s42, 0x24000
	s_addc_u32 s45, s43, 0
	s_add_u32 s46, s44, 0x24000
	s_addc_u32 s47, s45, 0
	s_add_u32 s10, s46, 0x24000
	s_addc_u32 s11, s47, 0
	s_add_u32 s22, s10, 0x24000
	s_addc_u32 s23, s11, 0
	global_load_dword v6, v4, s[8:9]
	global_load_dword v7, v4, s[8:9] offset:256
	global_load_dword v8, v4, s[14:15]
	global_load_dword v9, v4, s[14:15] offset:256
	global_load_dword v10, v4, s[16:17]
	global_load_dword v11, v4, s[16:17] offset:256
	global_load_dword v12, v4, s[18:19]
	global_load_dword v13, v4, s[18:19] offset:256
	global_load_dword v14, v4, s[20:21]
	global_load_dword v15, v4, s[20:21] offset:256
	global_load_dword v16, v4, s[26:27]
	global_load_dword v17, v4, s[26:27] offset:256
	global_load_dword v18, v4, s[28:29]
	global_load_dword v19, v4, s[28:29] offset:256
	global_load_dword v20, v4, s[30:31]
	global_load_dword v21, v4, s[30:31] offset:256
	global_load_dword v22, v4, s[34:35]
	global_load_dword v23, v4, s[34:35] offset:256
	global_load_dword v24, v4, s[36:37]
	global_load_dword v25, v4, s[36:37] offset:256
	global_load_dword v26, v4, s[38:39]
	global_load_dword v27, v4, s[38:39] offset:256
	global_load_dword v28, v4, s[40:41]
	global_load_dword v29, v4, s[40:41] offset:256
	global_load_dword v30, v4, s[42:43]
	global_load_dword v31, v4, s[42:43] offset:256
	global_load_dword v32, v4, s[44:45]
	global_load_dword v33, v4, s[44:45] offset:256
	global_load_dword v34, v4, s[46:47]
	global_load_dword v35, v4, s[46:47] offset:256
	global_load_dword v36, v4, s[10:11]
	global_load_dword v37, v4, s[10:11] offset:256
	global_load_dword v38, v4, s[22:23]
	global_load_dword v39, v4, s[22:23] offset:256
	s_waitcnt vmcnt(30)
	v_pk_add_f32 v[6:7], v[6:7], v[8:9]
	global_load_dword v40, v4, s[8:9] offset:512
	global_load_dword v41, v4, s[8:9] offset:768
	s_waitcnt vmcnt(30)
	v_pk_add_f32 v[6:7], v[6:7], v[10:11]
	global_load_dword v42, v4, s[14:15] offset:512
	global_load_dword v43, v4, s[14:15] offset:768
	s_waitcnt vmcnt(30)
	v_pk_add_f32 v[6:7], v[6:7], v[12:13]
	global_load_dword v44, v4, s[16:17] offset:512
	global_load_dword v45, v4, s[16:17] offset:768
	s_waitcnt vmcnt(30)
	v_pk_add_f32 v[6:7], v[6:7], v[14:15]
	global_load_dword v46, v4, s[18:19] offset:512
	global_load_dword v47, v4, s[18:19] offset:768
	s_waitcnt vmcnt(30)
	v_pk_add_f32 v[6:7], v[6:7], v[16:17]
	global_load_dword v48, v4, s[20:21] offset:512
	global_load_dword v49, v4, s[20:21] offset:768
	s_waitcnt vmcnt(30)
	v_pk_add_f32 v[6:7], v[6:7], v[18:19]
	global_load_dword v50, v4, s[26:27] offset:512
	global_load_dword v51, v4, s[26:27] offset:768
	s_waitcnt vmcnt(30)
	v_pk_add_f32 v[6:7], v[6:7], v[20:21]
	global_load_dword v52, v4, s[28:29] offset:512
	global_load_dword v53, v4, s[28:29] offset:768
	s_waitcnt vmcnt(30)
	v_pk_add_f32 v[6:7], v[6:7], v[22:23]
	global_load_dword v54, v4, s[30:31] offset:512
	global_load_dword v55, v4, s[30:31] offset:768
	s_waitcnt vmcnt(30)
	v_pk_add_f32 v[6:7], v[6:7], v[24:25]
	global_load_dword v56, v4, s[34:35] offset:512
	global_load_dword v57, v4, s[34:35] offset:768
	s_waitcnt vmcnt(30)
	v_pk_add_f32 v[6:7], v[6:7], v[26:27]
	global_load_dword v58, v4, s[36:37] offset:512
	global_load_dword v59, v4, s[36:37] offset:768
	s_waitcnt vmcnt(30)
	v_pk_add_f32 v[6:7], v[6:7], v[28:29]
	global_load_dword v60, v4, s[38:39] offset:512
	global_load_dword v61, v4, s[38:39] offset:768
	s_waitcnt vmcnt(30)
	v_pk_add_f32 v[6:7], v[6:7], v[30:31]
	global_load_dword v62, v4, s[40:41] offset:512
	global_load_dword v63, v4, s[40:41] offset:768
	s_waitcnt vmcnt(30)
	v_pk_add_f32 v[6:7], v[6:7], v[32:33]
	global_load_dword v64, v4, s[42:43] offset:512
	global_load_dword v65, v4, s[42:43] offset:768
	s_waitcnt vmcnt(30)
	v_pk_add_f32 v[6:7], v[6:7], v[34:35]
	global_load_dword v66, v4, s[44:45] offset:512
	global_load_dword v67, v4, s[44:45] offset:768
	s_waitcnt vmcnt(30)
	v_pk_add_f32 v[6:7], v[6:7], v[36:37]
	global_load_dword v68, v4, s[46:47] offset:512
	global_load_dword v69, v4, s[46:47] offset:768
	s_waitcnt vmcnt(30)
	v_pk_add_f32 v[6:7], v[6:7], v[38:39]
	global_load_dword v70, v4, s[10:11] offset:512
	global_load_dword v71, v4, s[10:11] offset:768
	global_load_dword v72, v4, s[22:23] offset:512
	global_load_dword v73, v4, s[22:23] offset:768
	v_max_f32_e64 v3, v3, |v6|
	v_max_f32_e64 v3, v3, |v7|
	s_waitcnt vmcnt(30)
	v_pk_add_f32 v[40:41], v[40:41], v[42:43]
	s_waitcnt vmcnt(28)
	v_pk_add_f32 v[40:41], v[40:41], v[44:45]
	s_waitcnt vmcnt(26)
	v_pk_add_f32 v[40:41], v[40:41], v[46:47]
	s_waitcnt vmcnt(24)
	v_pk_add_f32 v[40:41], v[40:41], v[48:49]
	s_waitcnt vmcnt(22)
	v_pk_add_f32 v[40:41], v[40:41], v[50:51]
	s_waitcnt vmcnt(20)
	v_pk_add_f32 v[40:41], v[40:41], v[52:53]
	s_waitcnt vmcnt(18)
	v_pk_add_f32 v[40:41], v[40:41], v[54:55]
	s_waitcnt vmcnt(16)
	v_pk_add_f32 v[40:41], v[40:41], v[56:57]
	s_waitcnt vmcnt(14)
	v_pk_add_f32 v[40:41], v[40:41], v[58:59]
	s_waitcnt vmcnt(12)
	v_pk_add_f32 v[40:41], v[40:41], v[60:61]
	s_waitcnt vmcnt(10)
	v_pk_add_f32 v[40:41], v[40:41], v[62:63]
	s_waitcnt vmcnt(8)
	v_pk_add_f32 v[40:41], v[40:41], v[64:65]
	s_waitcnt vmcnt(6)
	v_pk_add_f32 v[40:41], v[40:41], v[66:67]
	s_waitcnt vmcnt(4)
	v_pk_add_f32 v[40:41], v[40:41], v[68:69]
	s_waitcnt vmcnt(2)
	v_pk_add_f32 v[40:41], v[40:41], v[70:71]
	s_waitcnt vmcnt(0)
	v_pk_add_f32 v[40:41], v[40:41], v[72:73]
	v_max_f32_e64 v3, v3, |v40|
	v_max_f32_e64 v3, v3, |v41|
	ds_write_b32 v5, v3
	s_waitcnt lgkmcnt(0)
	s_barrier
	s_cmp_lg_u32 s5, 0
	s_cbranch_scc1 .LBB0_143
	v_lshlrev_b32_e32 v5, 5, v2
	v_lshlrev_b32_e32 v14, 2, v2
	ds_read_b128 v[6:9], v5
	ds_read_b128 v[10:13], v5 offset:16
	s_waitcnt lgkmcnt(0)
	v_max_f32_e32 v6, v6, v7
	v_max_f32_e32 v8, v8, v9
	v_max_f32_e32 v10, v10, v11
	v_max_f32_e32 v12, v12, v13
	v_max_f32_e32 v6, v6, v8
	v_max_f32_e32 v10, v10, v12
	v_max_f32_e32 v3, v6, v10
	ds_write_b32 v14, v3 offset:2048
	s_waitcnt lgkmcnt(0)
	ds_read_b128 v[6:9], v5 offset:2048
	ds_read_b128 v[10:13], v5 offset:2064
	s_waitcnt lgkmcnt(0)
	v_max_f32_e32 v6, v6, v7
	v_max_f32_e32 v8, v8, v9
	v_max_f32_e32 v10, v10, v11
	v_max_f32_e32 v12, v12, v13
	v_max_f32_e32 v6, v6, v8
	v_max_f32_e32 v10, v10, v12
	v_max_f32_e32 v3, v6, v10
	ds_write_b32 v14, v3 offset:4096
	s_waitcnt lgkmcnt(0)
	ds_read_b128 v[6:9], v5 offset:4096
	ds_read_b128 v[10:13], v5 offset:4112
	s_waitcnt lgkmcnt(0)
	v_max_f32_e32 v6, v6, v7
	v_max_f32_e32 v8, v8, v9
	v_max_f32_e32 v10, v10, v11
	v_max_f32_e32 v12, v12, v13
	v_max_f32_e32 v6, v6, v8
	v_max_f32_e32 v10, v10, v12
	v_max_f32_e32 v3, v6, v10
	v_cmp_eq_u32_e32 vcc, 0, v2
	s_and_saveexec_b64 s[10:11], vcc
	s_lshl_b32 s4, s4, 2
	s_add_u32 s4, s6, s4
	s_addc_u32 s5, s7, 0
	v_mov_b32_e32 v2, 0x24000
	global_store_dword v2, v3, s[4:5]
	s_or_b64 exec, exec, s[10:11]
